# local barriers F->G, G->H, H->I, I->J, J->B (B->C stays global instead of J->B), guarded, with qk epilogue rewrite
# baseline (speedup 1.0000x reference)
; DI unsigned xb_ld(unsigned* p)              { return __hip_atomic_load(p, __ATOMIC_RELAXED, __HIP_MEMORY_SCOPE_AGENT); }
; DI unsigned xb_add(unsigned* p, unsigned v) { return __hip_atomic_fetch_add(p, v, __ATOMIC_RELAXED, __HIP_MEMORY_SCOPE_AGENT); }
; #define XB_SPIN(cond, bar) do { unsigned _sp = 0; while (cond) { __builtin_amdgcn_s_sleep(1); \
;     if ((++_sp & 255u) == 0u) { if (xb_ld(&(bar)[XB_TMO])) break; if (_sp > XB_SPIN_CAP) { atomicAdd(&(bar)[XB_TMO], 1u); break; } } } } while (0)
; DI void xcd_barrier(const XcdBarrier& b) {
;     ...
;     const unsigned old = xb_add(&bar[XB_XSUB(b.x)], 1u);
;     const unsigned gen = old / nloc;
;     if (old + 1u == (gen + 1u) * nloc) {
;       __builtin_amdgcn_fence(__ATOMIC_RELEASE, "agent");
;       asm volatile("s_waitcnt vmcnt(0)" ::: "memory");
;       const unsigned og = xb_add(&bar[XB_TOP], 1u);
;       const unsigned tg = og / nx;
;       if (og + 1u == (tg + 1u) * nx) xb_add(&bar[XB_TOPGEN], 1u);
;       else XB_SPIN(xb_ld(&bar[XB_TOPGEN]) == tg, bar);
;       __builtin_amdgcn_fence(__ATOMIC_ACQUIRE, "agent");
;       xb_add(&bar[XB_XGEN(b.x)], 1u);
;       asm volatile("s_waitcnt vmcnt(0)" ::: "memory");
.LBB0_1343:
	s_mov_b64 s[24:25], exec
	buffer_wbl2 sc1
	s_waitcnt lgkmcnt(0)
	s_waitcnt vmcnt(0)
	s_cmp_eq_u32 s32, 0
	s_cbranch_scc1 .LBB0_1359
	v_mbcnt_lo_u32_b32 v0, s24, 0
	v_mbcnt_hi_u32_b32 v0, s25, v0
	v_cmp_eq_u32_e32 vcc, 0, v0
	s_and_saveexec_b64 s[26:27], vcc
	s_cbranch_execz .LBB0_1345
	s_bcnt1_i32_b64 s9, s[24:25]
	v_readlane_b32 s24, v244, 3
	v_mov_b32_e32 v3, s9
	v_readlane_b32 s25, v244, 4
	s_nop 4
	global_atomic_add v3, v1, v3, s[24:25] sc0
